# pool items: trailing-window sums on the matrix core (0/1 band operand in bf16 x transposed token rows, f32 accumulate, one K=32 step per 16x16 tile) instead of the win-iteration VALU loop
# speedup vs baseline: 1.0116x; 1.0116x over previous
.LBB0_1245:
	s_or_b64 exec, exec, s[10:11]
	s_movk_i32 s2, 0x1000
	v_add_co_u32_e32 v2, vcc, s2, v0
	s_movk_i32 s2, 0x3000
	s_nop 0
	v_addc_co_u32_e32 v3, vcc, 0, v1, vcc
	v_add_co_u32_e32 v126, vcc, s1, v0
	global_load_dwordx4 v[122:125], v[0:1], off
	global_load_dwordx4 v[118:121], v[0:1], off offset:64
	global_load_dwordx4 v[114:117], v[0:1], off offset:128
	global_load_dwordx4 v[110:113], v[0:1], off offset:192
	v_addc_co_u32_e32 v127, vcc, 0, v1, vcc
	v_add_co_u32_e32 v4, vcc, s2, v0
	s_movk_i32 s2, 0x4000
	s_nop 0
	v_addc_co_u32_e32 v5, vcc, 0, v1, vcc
	v_add_co_u32_e32 v6, vcc, s2, v0
	s_movk_i32 s2, 0x5000
	s_nop 0
	v_addc_co_u32_e32 v7, vcc, 0, v1, vcc
	global_load_dwordx4 v[106:109], v[2:3], off offset:64
	global_load_dwordx4 v[102:105], v[2:3], off offset:128
	global_load_dwordx4 v[98:101], v[126:127], off
	global_load_dwordx4 v[94:97], v[126:127], off offset:64
	global_load_dwordx4 v[90:93], v[126:127], off offset:128
	global_load_dwordx4 v[24:27], v[126:127], off offset:192
	global_load_dwordx4 v[28:31], v[2:3], off offset:192
	global_load_dwordx4 v[82:85], v[4:5], off offset:64
	global_load_dwordx4 v[78:81], v[4:5], off offset:128
	global_load_dwordx4 v[16:19], v[4:5], off offset:192
	global_load_dwordx4 v[86:89], v[6:7], off offset:-4096
	global_load_dwordx4 v[74:77], v[6:7], off
	global_load_dwordx4 v[70:73], v[6:7], off offset:64
	global_load_dwordx4 v[66:69], v[6:7], off offset:128
	v_add_co_u32_e32 v2, vcc, s2, v0
	s_movk_i32 s2, 0x6000
	s_nop 0
	v_addc_co_u32_e32 v3, vcc, 0, v1, vcc
	v_add_co_u32_e32 v4, vcc, s2, v0
	v_readlane_b32 s8, v253, 23
	s_nop 0
	v_addc_co_u32_e32 v5, vcc, 0, v1, vcc
	global_load_dwordx4 v[20:23], v[6:7], off offset:192
	global_load_dwordx4 v[62:65], v[4:5], off offset:-4096
	global_load_dwordx4 v[58:61], v[2:3], off offset:64
	global_load_dwordx4 v[54:57], v[2:3], off offset:128
	global_load_dwordx4 v[50:53], v[4:5], off
	global_load_dwordx4 v[46:49], v[4:5], off offset:64
	global_load_dwordx4 v[42:45], v[4:5], off offset:128
	global_load_dwordx4 v[8:11], v[4:5], off offset:192
	v_add_co_u32_e32 v0, vcc, 0x7000, v0
	v_lshlrev_b32_e32 v130, 4, v165
	s_nop 0
	v_addc_co_u32_e32 v1, vcc, 0, v1, vcc
	global_load_dwordx4 v[12:15], v[2:3], off offset:192
	global_load_dwordx4 v[38:41], v[0:1], off
	global_load_dwordx4 v[34:37], v[0:1], off offset:64
	global_load_dwordx4 v[4:7], v[0:1], off offset:128
	s_nop 0
	global_load_dwordx4 v[126:129], v[126:127], off offset:-4096
	s_nop 0
	global_load_dwordx4 v[0:3], v[0:1], off offset:192
	v_mov_b32_e32 v131, v33
	v_readlane_b32 s9, v253, 24
	s_movk_i32 s2, 0x8f0
	v_readfirstlane_b32 s17, v164
	v_lshl_add_u64 v[136:137], s[8:9], 0, v[130:131]
	v_add_u32_e32 v134, 0, v130
	s_waitcnt vmcnt(32)
	s_movk_i32 s8, 0x8f0
	v_cmp_gt_i32_e32 vcc, s8, v164
	s_and_saveexec_b64 s[10:11], vcc
	ds_write_b128 v204, v[232:235]
	s_or_b64 exec, exec, s[10:11]
	s_movk_i32 s8, 0x6f0
	v_cmp_gt_i32_e32 vcc, s8, v164
	s_and_saveexec_b64 s[10:11], vcc
	ds_write_b128 v205, v[188:191]
	s_or_b64 exec, exec, s[10:11]
	s_movk_i32 s8, 0x4f0
	v_cmp_gt_i32_e32 vcc, s8, v164
	s_and_saveexec_b64 s[10:11], vcc
	ds_write_b128 v206, v[192:195]
	s_or_b64 exec, exec, s[10:11]
	s_movk_i32 s8, 0x2f0
	v_cmp_gt_i32_e32 vcc, s8, v164
	s_and_saveexec_b64 s[10:11], vcc
	ds_write_b128 v207, v[196:199]
	s_or_b64 exec, exec, s[10:11]
	s_movk_i32 s8, 0xf0
	v_cmp_gt_i32_e32 vcc, s8, v164
	s_and_saveexec_b64 s[10:11], vcc
	ds_write_b128 v208, v[200:203]
	s_or_b64 exec, exec, s[10:11]
	v_ashrrev_i32_e32 v168, 2, v164
	v_lshlrev_b32_e32 v130, 6, v164
	v_mul_lo_u32 v166, v168, s33
	v_and_b32_e32 v167, 0xc0, v130
	v_readlane_b32 s2, v254, 56
	v_mov_b32_e32 v130, 0
	v_mov_b32_e32 v131, v130
	v_add3_u32 v169, v166, v167, s2
	v_readlane_b32 s2, v253, 19
	v_mov_b32_e32 v160, v130
	v_mov_b32_e32 v161, v130
	v_mov_b32_e32 v158, v130
	v_mov_b32_e32 v159, v130
	v_mov_b32_e32 v156, v130
	v_mov_b32_e32 v157, v130
	v_mov_b32_e32 v154, v130
	v_mov_b32_e32 v155, v130
	v_mov_b32_e32 v152, v130
	v_mov_b32_e32 v153, v130
	v_mov_b32_e32 v150, v130
	v_mov_b32_e32 v151, v130
	v_mov_b32_e32 v148, v130
	v_mov_b32_e32 v149, v130
	v_mov_b32_e32 v146, v130
	v_mov_b32_e32 v147, v130
	v_mov_b32_e32 v144, v130
	v_mov_b32_e32 v145, v130
	v_mov_b32_e32 v142, v130
	v_mov_b32_e32 v143, v130
	v_mov_b32_e32 v140, v130
	v_mov_b32_e32 v141, v130
	v_mov_b32_e32 v138, v130
	v_mov_b32_e32 v139, v130
	v_mov_b32_e32 v136, v130
	v_mov_b32_e32 v137, v130
	v_mov_b32_e32 v134, v130
	v_mov_b32_e32 v135, v130
	v_mov_b32_e32 v132, v130
	v_mov_b32_e32 v133, v130
	s_waitcnt lgkmcnt(0)
	s_ashr_i32 s9, s17, 2
	v_and_or_b32 v227, s9, -16, v165
	v_readlane_b32 s9, v253, 30
	v_mov_b64_e32 v[244:245], s[24:25]
	v_lshlrev_b32_e32 v222, 3, v163
	s_nop 1
	v_add_u32_e32 v227, s9, v227
	v_add_co_u32_e32 v244, vcc, v244, v222
	v_readlane_b32 s9, v253, 21
	s_nop 1
	v_addc_co_u32_e32 v245, vcc, 0, v245, vcc
	s_nop 1
	v_mad_i64_i32 v[244:245], s[14:15], v227, s70, v[244:245]
	s_lshl_b32 s10, s9, 1
	s_add_u32 s10, s10, 0x11101000
	s_mov_b32 s11, 0
	v_lshl_add_u64 v[244:245], v[244:245], 0, s[10:11]
	global_load_dwordx2 v[204:205], v[244:245], off
	global_load_dwordx2 v[206:207], v[244:245], off offset:32
	global_load_dwordx2 v[208:209], v[244:245], off offset:64
	global_load_dwordx2 v[236:237], v[244:245], off offset:96
	global_load_dwordx2 v[238:239], v[244:245], off offset:128
	global_load_dwordx2 v[240:241], v[244:245], off offset:160
	global_load_dwordx2 v[242:243], v[244:245], off offset:192
	global_load_dwordx2 v[244:245], v[244:245], off offset:224
	v_readlane_b32 s10, v251, 6
	v_readlane_b32 s11, v251, 7
	s_lshl_b32 s9, s9, 2
	s_add_u32 s10, s10, s12
	s_addc_u32 s11, s11, s13
	s_add_u32 s10, s10, s9
	s_addc_u32 s11, s11, 0
	s_nop 4
	global_load_dwordx4 v[232:235], v32, s[10:11]
	global_load_dwordx4 v[188:191], v32, s[10:11] offset:64
	global_load_dwordx4 v[192:195], v32, s[10:11] offset:128
	global_load_dwordx4 v[196:199], v32, s[10:11] offset:192
	global_load_dwordx4 v[200:203], v32, s[10:11] offset:256
	global_load_dwordx4 v[210:213], v32, s[10:11] offset:320
	global_load_dwordx4 v[214:217], v32, s[10:11] offset:384
	global_load_dwordx4 v[228:231], v32, s[10:11] offset:448
	v_cmp_gt_u32_e32 vcc, 16, v164
	s_and_saveexec_b64 s[10:11], vcc
	v_lshlrev_b32_e32 v166, 4, v164
	v_mov_b32_e32 v168, 0
	v_mov_b32_e32 v169, 0
	v_mov_b32_e32 v170, 0
	v_mov_b32_e32 v171, 0
	ds_write_b128 v166, v[168:171] offset:38896
	s_or_b64 exec, exec, s[10:11]
	s_waitcnt lgkmcnt(0)
	s_barrier
	s_ashr_i32 s9, s17, 2
	v_lshrrev_b32_e32 v166, 2, v165
	v_lshl_add_u32 v166, v163, 3, v166
	v_add_u32_e32 v166, s9, v166
	v_and_b32_e32 v167, 3, v165
	v_mul_u32_u24_e32 v166, 0x110, v166
	v_lshl_add_u32 v166, v167, 3, v166
	v_add_u32_e32 v250, s9, v165
	v_lshlrev_b32_e32 v167, 3, v163
	v_sub_u32_e32 v167, v167, v165
	s_sub_i32 s9, s2, 16
	v_add_u32_e32 v167, s9, v167
	v_mov_b32_e32 v187, 0x3f80
	v_add_u32_e32 v172, 0, v167
	v_add_u32_e32 v173, 1, v167
	v_add_u32_e32 v174, 2, v167
	v_add_u32_e32 v175, 3, v167
	v_add_u32_e32 v176, 4, v167
	v_add_u32_e32 v177, 5, v167
	v_add_u32_e32 v178, 6, v167
	v_add_u32_e32 v179, 7, v167
	v_cmp_gt_u32_e32 vcc, s2, v172
	v_cmp_gt_u32_e64 s[10:11], s2, v173
	s_nop 1
	v_cndmask_b32_e32 v180, v33, v187, vcc
	v_cndmask_b32_e64 v186, v33, v187, s[10:11]
	v_lshl_or_b32 v168, v186, 16, v180
	v_cmp_gt_u32_e32 vcc, s2, v174
	v_cmp_gt_u32_e64 s[10:11], s2, v175
	s_nop 1
	v_cndmask_b32_e32 v181, v33, v187, vcc
	v_cndmask_b32_e64 v186, v33, v187, s[10:11]
	v_lshl_or_b32 v169, v186, 16, v181
	v_cmp_gt_u32_e32 vcc, s2, v176
	v_cmp_gt_u32_e64 s[10:11], s2, v177
	s_nop 1
	v_cndmask_b32_e32 v182, v33, v187, vcc
	v_cndmask_b32_e64 v186, v33, v187, s[10:11]
	v_lshl_or_b32 v170, v186, 16, v182
	v_cmp_gt_u32_e32 vcc, s2, v178
	v_cmp_gt_u32_e64 s[10:11], s2, v179
	s_nop 1
	v_cndmask_b32_e32 v183, v33, v187, vcc
	v_cndmask_b32_e64 v186, v33, v187, s[10:11]
	v_lshl_or_b32 v171, v186, 16, v183
	v_readlane_b32 s9, v253, 26
	s_nop 1
	v_add_u32_e32 v186, s9, v250
	v_min_i32_e32 v186, s2, v186
	v_cvt_f32_i32_e32 v186, v186
	v_mul_u32_u24_e32 v185, 0x110, v250
	v_lshl_add_u32 v185, v163, 3, v185
	v_rcp_f32_e32 v186, v186
	v_add_u32_e32 v184, 0xff0, v185
	ds_read_b64_tr_b16 v[172:173], v166
	ds_read_b64_tr_b16 v[174:175], v166 offset:1088
	ds_read_b64_tr_b16 v[176:177], v166 offset:32
	ds_read_b64_tr_b16 v[178:179], v166 offset:1120
	s_waitcnt lgkmcnt(0)
	v_mfma_f32_16x16x32_bf16 v[130:133], v[172:175], v[168:171], 0
	v_mfma_f32_16x16x32_bf16 v[134:137], v[176:179], v[168:171], 0
	s_nop 7
	ds_read_b64_tr_b16 v[172:173], v166 offset:64
	ds_read_b64_tr_b16 v[174:175], v166 offset:1152
	ds_read_b64_tr_b16 v[176:177], v166 offset:96
	ds_read_b64_tr_b16 v[178:179], v166 offset:1184
	s_waitcnt lgkmcnt(0)
	v_mfma_f32_16x16x32_bf16 v[138:141], v[172:175], v[168:171], 0
	v_mfma_f32_16x16x32_bf16 v[142:145], v[176:179], v[168:171], 0
	s_nop 7
	ds_read_b64_tr_b16 v[172:173], v166 offset:128
	ds_read_b64_tr_b16 v[174:175], v166 offset:1216
	ds_read_b64_tr_b16 v[176:177], v166 offset:160
	ds_read_b64_tr_b16 v[178:179], v166 offset:1248
	s_waitcnt lgkmcnt(0)
	v_mfma_f32_16x16x32_bf16 v[146:149], v[172:175], v[168:171], 0
	v_mfma_f32_16x16x32_bf16 v[150:153], v[176:179], v[168:171], 0
	s_nop 7
	ds_read_b64_tr_b16 v[172:173], v166 offset:192
	ds_read_b64_tr_b16 v[174:175], v166 offset:1280
	ds_read_b64_tr_b16 v[176:177], v166 offset:224
	ds_read_b64_tr_b16 v[178:179], v166 offset:1312
	s_waitcnt lgkmcnt(0)
	v_mfma_f32_16x16x32_bf16 v[154:157], v[172:175], v[168:171], 0
	v_mfma_f32_16x16x32_bf16 v[158:161], v[176:179], v[168:171], 0
	s_nop 7
	ds_read_b64 v[172:173], v184
	ds_read_b64 v[174:175], v184 offset:32
	ds_read_b64 v[176:177], v184 offset:64
	ds_read_b64 v[178:179], v184 offset:96
	s_nop 7
	s_waitcnt lgkmcnt(0)
	v_lshlrev_b32_e32 v168, 16, v172
	v_and_b32_e32 v169, 0xffff0000, v172
	v_lshlrev_b32_e32 v170, 16, v173
	v_and_b32_e32 v171, 0xffff0000, v173
	v_fma_f32 v130, v186, v130, -v168
	v_fma_f32 v131, v186, v131, -v169
	v_fma_f32 v132, v186, v132, -v170
	v_fma_f32 v133, v186, v133, -v171
	v_cvt_pk_bf16_f32 v130, v130, v131
	v_cvt_pk_bf16_f32 v131, v132, v133
	ds_write_b64 v185, v[130:131] offset:40960
	v_lshlrev_b32_e32 v168, 16, v174
	v_and_b32_e32 v169, 0xffff0000, v174
	v_lshlrev_b32_e32 v170, 16, v175
	v_and_b32_e32 v171, 0xffff0000, v175
	v_fma_f32 v134, v186, v134, -v168
	v_fma_f32 v135, v186, v135, -v169
	v_fma_f32 v136, v186, v136, -v170
	v_fma_f32 v137, v186, v137, -v171
	v_cvt_pk_bf16_f32 v134, v134, v135
	v_cvt_pk_bf16_f32 v135, v136, v137
	ds_write_b64 v185, v[134:135] offset:40992
	v_lshlrev_b32_e32 v168, 16, v176
	v_and_b32_e32 v169, 0xffff0000, v176
	v_lshlrev_b32_e32 v170, 16, v177
	v_and_b32_e32 v171, 0xffff0000, v177
	v_fma_f32 v138, v186, v138, -v168
	v_fma_f32 v139, v186, v139, -v169
	v_fma_f32 v140, v186, v140, -v170
	v_fma_f32 v141, v186, v141, -v171
	v_cvt_pk_bf16_f32 v138, v138, v139
	v_cvt_pk_bf16_f32 v139, v140, v141
	ds_write_b64 v185, v[138:139] offset:41024
	v_lshlrev_b32_e32 v168, 16, v178
	v_and_b32_e32 v169, 0xffff0000, v178
	v_lshlrev_b32_e32 v170, 16, v179
	v_and_b32_e32 v171, 0xffff0000, v179
	v_fma_f32 v142, v186, v142, -v168
	v_fma_f32 v143, v186, v143, -v169
	v_fma_f32 v144, v186, v144, -v170
	v_fma_f32 v145, v186, v145, -v171
	v_cvt_pk_bf16_f32 v142, v142, v143
	v_cvt_pk_bf16_f32 v143, v144, v145
	ds_write_b64 v185, v[142:143] offset:41056
	ds_read_b64 v[172:173], v184 offset:128
	ds_read_b64 v[174:175], v184 offset:160
	ds_read_b64 v[176:177], v184 offset:192
	ds_read_b64 v[178:179], v184 offset:224
	s_waitcnt lgkmcnt(0)
	v_lshlrev_b32_e32 v168, 16, v172
	v_and_b32_e32 v169, 0xffff0000, v172
	v_lshlrev_b32_e32 v170, 16, v173
	v_and_b32_e32 v171, 0xffff0000, v173
	v_fma_f32 v146, v186, v146, -v168
	v_fma_f32 v147, v186, v147, -v169
	v_fma_f32 v148, v186, v148, -v170
	v_fma_f32 v149, v186, v149, -v171
	v_cvt_pk_bf16_f32 v146, v146, v147
	v_cvt_pk_bf16_f32 v147, v148, v149
	ds_write_b64 v185, v[146:147] offset:41088
	v_lshlrev_b32_e32 v168, 16, v174
	v_and_b32_e32 v169, 0xffff0000, v174
	v_lshlrev_b32_e32 v170, 16, v175
	v_and_b32_e32 v171, 0xffff0000, v175
	v_fma_f32 v150, v186, v150, -v168
	v_fma_f32 v151, v186, v151, -v169
	v_fma_f32 v152, v186, v152, -v170
	v_fma_f32 v153, v186, v153, -v171
	v_cvt_pk_bf16_f32 v150, v150, v151
	v_cvt_pk_bf16_f32 v151, v152, v153
	ds_write_b64 v185, v[150:151] offset:41120
	v_lshlrev_b32_e32 v168, 16, v176
	v_and_b32_e32 v169, 0xffff0000, v176
	v_lshlrev_b32_e32 v170, 16, v177
	v_and_b32_e32 v171, 0xffff0000, v177
	v_fma_f32 v154, v186, v154, -v168
	v_fma_f32 v155, v186, v155, -v169
	v_fma_f32 v156, v186, v156, -v170
	v_fma_f32 v157, v186, v157, -v171
	v_cvt_pk_bf16_f32 v154, v154, v155
	v_cvt_pk_bf16_f32 v155, v156, v157
	ds_write_b64 v185, v[154:155] offset:41152
	v_lshlrev_b32_e32 v168, 16, v178
	v_and_b32_e32 v169, 0xffff0000, v178
	v_lshlrev_b32_e32 v170, 16, v179
	v_and_b32_e32 v171, 0xffff0000, v179
	v_fma_f32 v158, v186, v158, -v168
	v_fma_f32 v159, v186, v159, -v169
	v_fma_f32 v160, v186, v160, -v170
	v_fma_f32 v161, v186, v161, -v171
	v_cvt_pk_bf16_f32 v158, v158, v159
	v_cvt_pk_bf16_f32 v159, v160, v161
	ds_write_b64 v185, v[158:159] offset:41184
	s_waitcnt lgkmcnt(0)
	v_readlane_b32 s48, v251, 4
	v_readlane_b32 s50, v251, 6
	v_readlane_b32 s51, v251, 7
	s_mov_b64 s[74:75], s[50:51]
	s_add_u32 s2, s74, s12
	s_addc_u32 s14, s75, s13
	s_ashr_i32 s8, s17, 2
	s_mov_b64 s[10:11], 0x11101000
	v_readlane_b32 s49, v251, 5
	v_and_or_b32 v142, s8, -16, v165
	v_mul_lo_u32 v250, v142, s33
	v_and_b32_e32 v167, 48, v164
	v_add3_u32 v143, 0, v250, v167
	s_waitcnt lgkmcnt(0)
	s_barrier
	ds_read_b128 v[134:137], v143 offset:40960
	ds_read_b128 v[130:133], v143 offset:41024
	s_waitcnt vmcnt(47) lgkmcnt(1)
	v_mfma_f32_16x16x32_bf16 v[122:125], v[122:125], v[134:137], 0
	v_readlane_b32 s8, v253, 30
	v_mov_b32_e32 v164, v218
	v_readlane_b32 s52, v251, 8
	s_waitcnt vmcnt(46) lgkmcnt(0)
	v_mfma_f32_16x16x32_bf16 v[138:141], v[118:121], v[130:133], v[122:125]
	s_nop 2
	ds_read_b128 v[122:125], v143 offset:41088
	ds_read_b128 v[118:121], v143 offset:41152
	v_readlane_b32 s53, v251, 9
	v_readlane_b32 s54, v251, 10
	s_waitcnt vmcnt(45) lgkmcnt(1)
	v_mfma_f32_16x16x32_bf16 v[114:117], v[114:117], v[122:125], v[138:141]
	v_readlane_b32 s55, v251, 11
	v_readlane_b32 s56, v251, 12
	v_readlane_b32 s57, v251, 13
	s_waitcnt vmcnt(44) lgkmcnt(0)
	v_mfma_f32_16x16x32_bf16 v[110:113], v[110:113], v[118:121], v[114:117]
	v_readlane_b32 s58, v251, 14
	v_readlane_b32 s59, v251, 15
	v_readlane_b32 s60, v251, 16
	s_waitcnt vmcnt(17)
	v_mfma_f32_16x16x32_bf16 v[114:117], v[126:129], v[134:137], 0
	v_readlane_b32 s61, v251, 17
	v_readlane_b32 s62, v251, 18
	v_readlane_b32 s63, v251, 19
	v_mfma_f32_16x16x32_bf16 v[106:109], v[106:109], v[130:133], v[114:117]
	v_mfma_f32_16x16x32_bf16 v[98:101], v[98:101], v[134:137], 0
	s_nop 2
	v_add_u32_e32 v114, s8, v142
	v_mfma_f32_16x16x32_bf16 v[102:105], v[102:105], v[122:125], v[106:109]
	s_nop 2
	v_mov_b64_e32 v[106:107], s[24:25]
	v_mad_i64_i32 v[106:107], s[8:9], v114, s70, v[106:107]
	v_mfma_f32_16x16x32_bf16 v[86:89], v[86:89], v[134:137], 0
	v_readlane_b32 s8, v253, 21
	s_lshl_b32 s28, s8, 1
	v_lshl_add_u64 v[106:107], v[106:107], 0, s[28:29]
	v_mfma_f32_16x16x32_bf16 v[96:99], v[94:97], v[130:133], v[98:101]
	v_lshlrev_b32_e32 v108, 3, v163
	v_mov_b32_e32 v109, v33
	s_mov_b32 s9, 0x11101000
	v_lshl_add_u64 v[100:101], v[106:107], 0, v[108:109]
	v_mfma_f32_16x16x32_bf16 v[84:87], v[82:85], v[130:133], v[86:89]
	s_lshl_b32 s8, s8, 2
	v_lshl_add_u64 v[94:95], v[100:101], 0, s[10:11]
	s_add_u32 s10, s2, s8
	v_mfma_f32_16x16x32_bf16 v[90:93], v[90:93], v[122:125], v[96:99]
	s_addc_u32 s11, s14, 0
	v_readlane_b32 s8, v253, 28
	s_or_b32 s8, s8, s16
	v_add_co_u32_e32 v96, vcc, s9, v100
	v_mfma_f32_16x16x32_bf16 v[78:81], v[78:81], v[122:125], v[84:87]
	s_nop 0
	v_addc_co_u32_e32 v97, vcc, 0, v101, vcc
	s_waitcnt vmcnt(0)
	s_nop 15
	v_mov_b64_e32 v[98:99], v[206:207]
	v_mov_b64_e32 v[100:101], v[208:209]
	v_mov_b64_e32 v[106:107], v[236:237]
	v_mov_b64_e32 v[108:109], v[238:239]
	v_mov_b64_e32 v[88:89], v[204:205]
	v_mov_b64_e32 v[114:115], v[240:241]
	v_mov_b64_e32 v[116:117], v[242:243]
	v_mov_b64_e32 v[82:83], v[244:245]
	s_nop 15
	v_mov_b64_e32 v[84:85], v[232:233]
	v_mov_b64_e32 v[86:87], v[234:235]
	v_mfma_f32_16x16x32_bf16 v[74:77], v[74:77], v[134:137], 0
	v_readlane_b32 s9, v252, 29
	s_add_u32 s8, s9, s8
	v_readlane_b32 s9, v252, 30
	v_mfma_f32_16x16x32_bf16 v[62:65], v[62:65], v[134:137], 0
	s_addc_u32 s9, s9, 0
	v_mfma_f32_16x16x32_bf16 v[70:73], v[70:73], v[130:133], v[74:77]
	v_mfma_f32_16x16x32_bf16 v[58:61], v[58:61], v[130:133], v[62:65]
	s_waitcnt vmcnt(4)
	s_nop 0
	v_lshlrev_b32_e32 v75, 16, v88
	v_mfma_f32_16x16x32_bf16 v[66:69], v[66:69], v[122:125], v[70:73]
	s_nop 0
	v_and_b32_e32 v64, 0xffff0000, v89
	s_waitcnt vmcnt(0)
	v_mul_f32_e32 v74, v110, v84
	v_mul_f32_e32 v70, v111, v85
	v_and_b32_e32 v71, 0xffff0000, v88
	v_mul_f32_e32 v70, v70, v71
	v_mul_f32_e32 v71, v112, v86
	v_lshlrev_b32_e32 v72, 16, v89
	v_mul_f32_e32 v63, v113, v87
	v_mul_f32_e32 v74, v74, v75
	v_cvt_pk_bf16_f32 v70, v74, v70
	v_mul_f32_e32 v62, v71, v72
	v_mfma_f32_16x16x32_bf16 v[54:57], v[54:57], v[122:125], v[58:61]
	s_nop 2
	v_mul_f32_e32 v58, v63, v64
	v_cvt_pk_bf16_f32 v71, v62, v58
	global_store_dwordx2 v[96:97], v[70:71], off
	v_mov_b64_e32 v[58:59], v[188:189]
	v_mov_b64_e32 v[60:61], v[190:191]
	v_mfma_f32_16x16x32_bf16 v[50:53], v[50:53], v[134:137], 0
	v_lshlrev_b32_e32 v62, 16, v98
	v_mfma_f32_16x16x32_bf16 v[28:31], v[28:31], v[118:121], v[102:105]
	v_mfma_f32_16x16x32_bf16 v[46:49], v[46:49], v[130:133], v[50:53]
	v_mfma_f32_16x16x32_bf16 v[42:45], v[42:45], v[122:125], v[46:49]
	s_nop 4
	v_mul_f32_e32 v28, v28, v58
	v_mul_f32_e32 v29, v29, v59
	v_and_b32_e32 v58, 0xffff0000, v98
	v_mul_f32_e32 v28, v28, v62
	v_mul_f32_e32 v29, v29, v58
	v_cvt_pk_bf16_f32 v50, v28, v29
	v_mul_f32_e32 v28, v30, v60
	v_lshlrev_b32_e32 v29, 16, v99
	v_mul_f32_e32 v46, v28, v29
	v_mul_f32_e32 v47, v31, v61
	v_mfma_f32_16x16x32_bf16 v[28:31], v[38:41], v[134:137], 0
	v_and_b32_e32 v48, 0xffff0000, v99
	v_mul_f32_e32 v38, v47, v48
	v_cvt_pk_bf16_f32 v51, v46, v38
	global_store_dwordx2 v[94:95], v[50:51], off offset:32
	v_mfma_f32_16x16x32_bf16 v[28:31], v[34:37], v[130:133], v[28:31]
	v_mov_b64_e32 v[34:35], v[192:193]
	v_mov_b64_e32 v[36:37], v[194:195]
	v_lshlrev_b32_e32 v38, 16, v100
	v_and_b32_e32 v39, 0xffff0000, v100
	v_mfma_f32_16x16x32_bf16 v[24:27], v[24:27], v[118:121], v[90:93]
	v_lshlrev_b32_e32 v40, 16, v101
	v_and_b32_e32 v41, 0xffff0000, v101
	v_mov_b32_e32 v131, v33
	v_mfma_f32_16x16x32_bf16 v[16:19], v[16:19], v[118:121], v[78:81]
	v_mfma_f32_16x16x32_bf16 v[20:23], v[20:23], v[118:121], v[66:69]
	s_nop 1
	v_mul_f32_e32 v24, v24, v34
	v_mul_f32_e32 v25, v25, v35
	v_mul_f32_e32 v26, v26, v36
	v_mul_f32_e32 v27, v27, v37
	v_mul_f32_e32 v24, v24, v38
	v_mul_f32_e32 v25, v25, v39
	v_mul_f32_e32 v26, v26, v40
	v_mul_f32_e32 v27, v27, v41
	v_cvt_pk_bf16_f32 v24, v24, v25
	v_cvt_pk_bf16_f32 v25, v26, v27
	global_store_dwordx2 v[94:95], v[24:25], off offset:64
	v_mov_b64_e32 v[24:25], v[196:197]
	v_mov_b64_e32 v[26:27], v[198:199]
	v_lshlrev_b32_e32 v34, 16, v106
	v_and_b32_e32 v35, 0xffff0000, v106
	v_lshlrev_b32_e32 v36, 16, v107
	v_and_b32_e32 v37, 0xffff0000, v107
	v_mfma_f32_16x16x32_bf16 v[12:15], v[12:15], v[118:121], v[54:57]
	v_mul_f32_e32 v16, v16, v24
	v_mul_f32_e32 v17, v17, v25
	v_mul_f32_e32 v18, v18, v26
	v_mul_f32_e32 v19, v19, v27
	v_mul_f32_e32 v16, v16, v34
	v_mul_f32_e32 v17, v17, v35
	v_mul_f32_e32 v18, v18, v36
	v_mul_f32_e32 v19, v19, v37
	v_cvt_pk_bf16_f32 v16, v16, v17
	v_cvt_pk_bf16_f32 v17, v18, v19
	global_store_dwordx2 v[94:95], v[16:17], off offset:96
	v_mov_b64_e32 v[16:17], v[200:201]
	v_mov_b64_e32 v[18:19], v[202:203]
	v_lshlrev_b32_e32 v24, 16, v108
	v_and_b32_e32 v25, 0xffff0000, v108
	v_lshlrev_b32_e32 v26, 16, v109
	v_and_b32_e32 v27, 0xffff0000, v109
	v_mfma_f32_16x16x32_bf16 v[8:11], v[8:11], v[118:121], v[42:45]
	v_mul_f32_e32 v16, v20, v16
	v_mul_f32_e32 v17, v21, v17
	v_mul_f32_e32 v18, v22, v18
	v_mul_f32_e32 v19, v23, v19
	v_mul_f32_e32 v16, v16, v24
	v_mul_f32_e32 v17, v17, v25
	v_mul_f32_e32 v18, v18, v26
	v_mul_f32_e32 v19, v19, v27
	v_cvt_pk_bf16_f32 v16, v16, v17
	v_cvt_pk_bf16_f32 v17, v18, v19
	global_store_dwordx2 v[94:95], v[16:17], off offset:128
	v_mov_b64_e32 v[16:17], v[210:211]
	v_mov_b64_e32 v[18:19], v[212:213]
	v_lshlrev_b32_e32 v20, 16, v114
	v_and_b32_e32 v21, 0xffff0000, v114
	v_lshlrev_b32_e32 v22, 16, v115
	v_and_b32_e32 v23, 0xffff0000, v115
	v_mfma_f32_16x16x32_bf16 v[4:7], v[4:7], v[122:125], v[28:31]
	v_mul_f32_e32 v12, v12, v16
	v_mul_f32_e32 v13, v13, v17
	v_mul_f32_e32 v14, v14, v18
	v_mul_f32_e32 v15, v15, v19
	v_mul_f32_e32 v12, v12, v20
	v_mul_f32_e32 v13, v13, v21
	v_mul_f32_e32 v14, v14, v22
	v_mul_f32_e32 v15, v15, v23
	v_cvt_pk_bf16_f32 v12, v12, v13
	v_cvt_pk_bf16_f32 v13, v14, v15
	global_store_dwordx2 v[94:95], v[12:13], off offset:160
	v_mov_b64_e32 v[12:13], v[214:215]
	v_mov_b64_e32 v[14:15], v[216:217]
	v_lshlrev_b32_e32 v16, 16, v116
	v_and_b32_e32 v17, 0xffff0000, v116
	v_lshlrev_b32_e32 v18, 16, v117
	v_and_b32_e32 v19, 0xffff0000, v117
	v_mfma_f32_16x16x32_bf16 v[0:3], v[0:3], v[118:121], v[4:7]
	v_mul_f32_e32 v8, v8, v12
	v_mul_f32_e32 v9, v9, v13
	v_mul_f32_e32 v10, v10, v14
	v_mul_f32_e32 v11, v11, v15
	v_mul_f32_e32 v8, v8, v16
	v_mul_f32_e32 v9, v9, v17
	v_mul_f32_e32 v10, v10, v18
	v_mul_f32_e32 v11, v11, v19
	v_cvt_pk_bf16_f32 v8, v8, v9
	v_cvt_pk_bf16_f32 v9, v10, v11
	global_store_dwordx2 v[94:95], v[8:9], off offset:192
	v_mov_b64_e32 v[8:9], v[228:229]
	v_mov_b64_e32 v[10:11], v[230:231]
	v_lshlrev_b32_e32 v4, 16, v82
	v_and_b32_e32 v5, 0xffff0000, v82
	v_lshlrev_b32_e32 v6, 16, v83
	v_and_b32_e32 v7, 0xffff0000, v83
	v_mul_f32_e32 v0, v0, v8
	v_mul_f32_e32 v1, v1, v9
	v_mul_f32_e32 v2, v2, v10
	v_mul_f32_e32 v3, v3, v11
	v_mul_f32_e32 v0, v0, v4
	v_mul_f32_e32 v1, v1, v5
	v_mul_f32_e32 v2, v2, v6
	v_mul_f32_e32 v3, v3, v7
	v_cvt_pk_bf16_f32 v0, v0, v1
	v_cvt_pk_bf16_f32 v1, v2, v3
	global_store_dwordx2 v[94:95], v[0:1], off offset:224
	s_barrier
	s_nop 0
	v_and_b32_e32 v165, 15, v164
	v_bfe_u32 v163, v164, 4, 2
	v_lshlrev_b32_e32 v32, 8, v165
	v_lshl_add_u64 v[0:1], s[8:9], 0, v[32:33]
	v_lshlrev_b32_e32 v32, 4, v163
	v_lshl_add_u64 v[0:1], v[0:1], 0, v[32:33]
	v_readlane_b32 s8, v253, 35
	v_readlane_b32 s9, v253, 36
	v_lshlrev_b32_e32 v130, 4, v165
	v_mov_b32_e32 v131, v33
	s_nop 1
	v_lshl_add_u64 v[136:137], s[8:9], 0, v[130:131]
	v_add_u32_e32 v134, 0, v130
	s_movk_i32 s8, 0x8f0
	v_cmp_gt_i32_e32 vcc, s8, v164
	s_and_saveexec_b64 s[10:11], vcc
	v_readlane_b32 s86, v254, 59
	v_readlane_b32 s84, v254, 61
	v_readlane_b32 s87, v254, 60
	v_readlane_b32 s85, v254, 62
	s_cbranch_execz .LBB0_1251
	v_ashrrev_i32_e32 v135, 4, v164
	v_readlane_b32 s8, v253, 38
	v_mov_b32_e32 v232, 0
	v_mov_b32_e32 v233, 0
	v_cmp_lt_i32_e32 vcc, s8, v135
	v_mov_b32_e32 v234, 0
	v_mov_b32_e32 v235, 0
	s_and_saveexec_b64 s[12:13], vcc
	s_cbranch_execz .LBB0_1250
	v_readlane_b32 s8, v253, 37
	s_nop 1
	v_add_u32_e32 v232, s8, v135
	v_mad_i64_i32 v[232:233], s[8:9], v232, s70, v[136:137]
	global_load_dwordx4 v[232:235], v[232:233], off

.LBB0_1267:
	s_or_b64 exec, exec, s[10:11]
	s_movk_i32 s8, 0x1000
	v_add_co_u32_e32 v2, vcc, s8, v0
	s_movk_i32 s8, 0x3000
	s_nop 0
	v_addc_co_u32_e32 v3, vcc, 0, v1, vcc
	v_add_co_u32_e32 v12, vcc, s1, v0
	global_load_dwordx4 v[114:117], v[0:1], off
	global_load_dwordx4 v[110:113], v[0:1], off offset:64
	global_load_dwordx4 v[106:109], v[0:1], off offset:128
	global_load_dwordx4 v[102:105], v[0:1], off offset:192
	v_addc_co_u32_e32 v13, vcc, 0, v1, vcc
	v_add_co_u32_e32 v4, vcc, s8, v0
	s_movk_i32 s8, 0x4000
	s_nop 0
	v_addc_co_u32_e32 v5, vcc, 0, v1, vcc
	v_add_co_u32_e32 v6, vcc, s8, v0
	s_movk_i32 s8, 0x5000
	s_nop 0
	v_addc_co_u32_e32 v7, vcc, 0, v1, vcc
	global_load_dwordx4 v[122:125], v[2:3], off offset:64
	global_load_dwordx4 v[118:121], v[2:3], off offset:128
	global_load_dwordx4 v[98:101], v[12:13], off
	global_load_dwordx4 v[94:97], v[12:13], off offset:64
	global_load_dwordx4 v[90:93], v[12:13], off offset:128
	global_load_dwordx4 v[20:23], v[12:13], off offset:192
	global_load_dwordx4 v[38:41], v[2:3], off offset:192
	global_load_dwordx4 v[78:81], v[4:5], off offset:64
	global_load_dwordx4 v[74:77], v[4:5], off offset:128
	global_load_dwordx4 v[16:19], v[4:5], off offset:192
	global_load_dwordx4 v[82:85], v[6:7], off offset:-4096
	global_load_dwordx4 v[70:73], v[6:7], off
	global_load_dwordx4 v[66:69], v[6:7], off offset:64
	global_load_dwordx4 v[58:61], v[6:7], off offset:128
	v_add_co_u32_e32 v8, vcc, s8, v0
	s_movk_i32 s8, 0x6000
	s_nop 0
	v_addc_co_u32_e32 v9, vcc, 0, v1, vcc
	v_add_co_u32_e32 v2, vcc, s8, v0
	global_load_dwordx4 v[62:65], v[8:9], off offset:64
	global_load_dwordx4 v[50:53], v[8:9], off offset:128
	v_addc_co_u32_e32 v3, vcc, 0, v1, vcc
	v_add_co_u32_e32 v14, vcc, 0x7000, v0
	global_load_dwordx4 v[34:37], v[6:7], off offset:192
	global_load_dwordx4 v[86:89], v[2:3], off offset:-4096
	global_load_dwordx4 v[54:57], v[2:3], off
	global_load_dwordx4 v[46:49], v[2:3], off offset:64
	global_load_dwordx4 v[42:45], v[2:3], off offset:128
	global_load_dwordx4 v[24:27], v[2:3], off offset:192
	v_addc_co_u32_e32 v15, vcc, 0, v1, vcc
	global_load_dwordx4 v[28:31], v[8:9], off offset:192
	s_nop 0
	global_load_dwordx4 v[8:11], v[14:15], off
	global_load_dwordx4 v[4:7], v[14:15], off offset:64
	global_load_dwordx4 v[0:3], v[14:15], off offset:128
	global_load_dwordx4 v[126:129], v[12:13], off offset:-4096
	s_nop 0
	global_load_dwordx4 v[12:15], v[14:15], off offset:192
	v_readlane_b32 s8, v253, 35
	v_lshlrev_b32_e32 v130, 4, v165
	v_readlane_b32 s9, v253, 36
	v_readfirstlane_b32 s15, v164
	v_add_u32_e32 v134, 0, v130
	v_lshl_add_u64 v[136:137], s[8:9], 0, v[130:131]
	s_movk_i32 s8, 0x8f0
	s_waitcnt vmcnt(32)
	s_movk_i32 s8, 0x8f0
	v_cmp_gt_i32_e32 vcc, s8, v164
	s_and_saveexec_b64 s[10:11], vcc
	ds_write_b128 v204, v[232:235]
	s_or_b64 exec, exec, s[10:11]
	s_movk_i32 s8, 0x6f0
	v_cmp_gt_i32_e32 vcc, s8, v164
	s_and_saveexec_b64 s[10:11], vcc
	ds_write_b128 v205, v[188:191]
	s_or_b64 exec, exec, s[10:11]
	s_movk_i32 s8, 0x4f0
	v_cmp_gt_i32_e32 vcc, s8, v164
	s_and_saveexec_b64 s[10:11], vcc
	ds_write_b128 v206, v[192:195]
	s_or_b64 exec, exec, s[10:11]
	s_movk_i32 s8, 0x2f0
	v_cmp_gt_i32_e32 vcc, s8, v164
	s_and_saveexec_b64 s[10:11], vcc
	ds_write_b128 v207, v[196:199]
	s_or_b64 exec, exec, s[10:11]
	s_movk_i32 s8, 0xf0
	v_cmp_gt_i32_e32 vcc, s8, v164
	s_and_saveexec_b64 s[10:11], vcc
	ds_write_b128 v208, v[200:203]
	s_or_b64 exec, exec, s[10:11]
	v_ashrrev_i32_e32 v168, 2, v164
	v_lshlrev_b32_e32 v130, 6, v164
	v_mul_lo_u32 v166, v168, s33
	v_and_b32_e32 v167, 0xc0, v130
	v_readlane_b32 s8, v254, 56
	v_mov_b32_e32 v130, 0
	v_mov_b32_e32 v131, v130
	v_add3_u32 v169, v166, v167, s8
	v_readlane_b32 s8, v253, 27
	v_mov_b32_e32 v160, v130
	v_mov_b32_e32 v161, v130
	v_mov_b32_e32 v158, v130
	v_mov_b32_e32 v159, v130
	v_mov_b32_e32 v156, v130
	v_mov_b32_e32 v157, v130
	v_mov_b32_e32 v154, v130
	v_mov_b32_e32 v155, v130
	v_mov_b32_e32 v152, v130
	v_mov_b32_e32 v153, v130
	v_mov_b32_e32 v150, v130
	v_mov_b32_e32 v151, v130
	v_mov_b32_e32 v148, v130
	v_mov_b32_e32 v149, v130
	v_mov_b32_e32 v146, v130
	v_mov_b32_e32 v147, v130
	v_mov_b32_e32 v144, v130
	v_mov_b32_e32 v145, v130
	v_mov_b32_e32 v142, v130
	v_mov_b32_e32 v143, v130
	v_mov_b32_e32 v140, v130
	v_mov_b32_e32 v141, v130
	v_mov_b32_e32 v138, v130
	v_mov_b32_e32 v139, v130
	v_mov_b32_e32 v136, v130
	v_mov_b32_e32 v137, v130
	v_mov_b32_e32 v134, v130
	v_mov_b32_e32 v135, v130
	v_mov_b32_e32 v132, v130
	v_mov_b32_e32 v133, v130
	s_waitcnt lgkmcnt(0)
	s_ashr_i32 s9, s15, 2
	v_and_or_b32 v227, s9, -16, v165
	v_readlane_b32 s9, v253, 32
	v_mov_b64_e32 v[244:245], s[24:25]
	v_lshlrev_b32_e32 v222, 3, v163
	s_nop 1
	v_add_u32_e32 v227, s9, v227
	v_add_co_u32_e32 v244, vcc, v244, v222
	v_readlane_b32 s9, v253, 29
	s_nop 1
	v_addc_co_u32_e32 v245, vcc, 0, v245, vcc
	s_nop 1
	v_mad_i64_i32 v[244:245], s[12:13], v227, s70, v[244:245]
	s_lshl_b32 s10, s9, 1
	s_add_u32 s10, s10, 0x11101000
	s_mov_b32 s11, 0
	v_lshl_add_u64 v[244:245], v[244:245], 0, s[10:11]
	global_load_dwordx2 v[204:205], v[244:245], off
	global_load_dwordx2 v[206:207], v[244:245], off offset:32
	global_load_dwordx2 v[208:209], v[244:245], off offset:64
	global_load_dwordx2 v[236:237], v[244:245], off offset:96
	global_load_dwordx2 v[238:239], v[244:245], off offset:128
	global_load_dwordx2 v[240:241], v[244:245], off offset:160
	global_load_dwordx2 v[242:243], v[244:245], off offset:192
	global_load_dwordx2 v[244:245], v[244:245], off offset:224
	s_lshl_b32 s9, s9, 2
	s_add_u32 s10, s2, s9
	s_addc_u32 s11, s14, 0
	s_nop 4
	global_load_dwordx4 v[232:235], v32, s[10:11]
	global_load_dwordx4 v[188:191], v32, s[10:11] offset:64
	global_load_dwordx4 v[192:195], v32, s[10:11] offset:128
	global_load_dwordx4 v[196:199], v32, s[10:11] offset:192
	global_load_dwordx4 v[200:203], v32, s[10:11] offset:256
	global_load_dwordx4 v[210:213], v32, s[10:11] offset:320
	global_load_dwordx4 v[214:217], v32, s[10:11] offset:384
	global_load_dwordx4 v[228:231], v32, s[10:11] offset:448
	v_cmp_gt_u32_e32 vcc, 16, v164
	s_and_saveexec_b64 s[10:11], vcc
	v_lshlrev_b32_e32 v166, 4, v164
	v_mov_b32_e32 v168, 0
	v_mov_b32_e32 v169, 0
	v_mov_b32_e32 v170, 0
	v_mov_b32_e32 v171, 0
	ds_write_b128 v166, v[168:171] offset:38896
	s_or_b64 exec, exec, s[10:11]
	s_waitcnt lgkmcnt(0)
	s_barrier
	s_ashr_i32 s9, s15, 2
	v_lshrrev_b32_e32 v166, 2, v165
	v_lshl_add_u32 v166, v163, 3, v166
	v_add_u32_e32 v166, s9, v166
	v_and_b32_e32 v167, 3, v165
	v_mul_u32_u24_e32 v166, 0x110, v166
	v_lshl_add_u32 v166, v167, 3, v166
	v_add_u32_e32 v250, s9, v165
	v_lshlrev_b32_e32 v167, 3, v163
	v_sub_u32_e32 v167, v167, v165
	s_sub_i32 s9, s8, 16
	v_add_u32_e32 v167, s9, v167
	v_mov_b32_e32 v187, 0x3f80
	v_add_u32_e32 v172, 0, v167
	v_add_u32_e32 v173, 1, v167
	v_add_u32_e32 v174, 2, v167
	v_add_u32_e32 v175, 3, v167
	v_add_u32_e32 v176, 4, v167
	v_add_u32_e32 v177, 5, v167
	v_add_u32_e32 v178, 6, v167
	v_add_u32_e32 v179, 7, v167
	v_cmp_gt_u32_e32 vcc, s8, v172
	v_cmp_gt_u32_e64 s[10:11], s8, v173
	s_nop 1
	v_cndmask_b32_e32 v180, v33, v187, vcc
	v_cndmask_b32_e64 v186, v33, v187, s[10:11]
	v_lshl_or_b32 v168, v186, 16, v180
	v_cmp_gt_u32_e32 vcc, s8, v174
	v_cmp_gt_u32_e64 s[10:11], s8, v175
	s_nop 1
	v_cndmask_b32_e32 v181, v33, v187, vcc
	v_cndmask_b32_e64 v186, v33, v187, s[10:11]
	v_lshl_or_b32 v169, v186, 16, v181
	v_cmp_gt_u32_e32 vcc, s8, v176
	v_cmp_gt_u32_e64 s[10:11], s8, v177
	s_nop 1
	v_cndmask_b32_e32 v182, v33, v187, vcc
	v_cndmask_b32_e64 v186, v33, v187, s[10:11]
	v_lshl_or_b32 v170, v186, 16, v182
	v_cmp_gt_u32_e32 vcc, s8, v178
	v_cmp_gt_u32_e64 s[10:11], s8, v179
	s_nop 1
	v_cndmask_b32_e32 v183, v33, v187, vcc
	v_cndmask_b32_e64 v186, v33, v187, s[10:11]
	v_lshl_or_b32 v171, v186, 16, v183
	v_readlane_b32 s9, v253, 39
	s_nop 1
	v_add_u32_e32 v186, s9, v250
	v_min_i32_e32 v186, s8, v186
	v_cvt_f32_i32_e32 v186, v186
	v_mul_u32_u24_e32 v185, 0x110, v250
	v_lshl_add_u32 v185, v163, 3, v185
	v_rcp_f32_e32 v186, v186
	v_add_u32_e32 v184, 0xff0, v185
	ds_read_b64_tr_b16 v[172:173], v166
	ds_read_b64_tr_b16 v[174:175], v166 offset:1088
	ds_read_b64_tr_b16 v[176:177], v166 offset:32
	ds_read_b64_tr_b16 v[178:179], v166 offset:1120
	s_waitcnt lgkmcnt(0)
	v_mfma_f32_16x16x32_bf16 v[130:133], v[172:175], v[168:171], 0
	v_mfma_f32_16x16x32_bf16 v[134:137], v[176:179], v[168:171], 0
	s_nop 7
	ds_read_b64_tr_b16 v[172:173], v166 offset:64
	ds_read_b64_tr_b16 v[174:175], v166 offset:1152
	ds_read_b64_tr_b16 v[176:177], v166 offset:96
	ds_read_b64_tr_b16 v[178:179], v166 offset:1184
	s_waitcnt lgkmcnt(0)
	v_mfma_f32_16x16x32_bf16 v[138:141], v[172:175], v[168:171], 0
	v_mfma_f32_16x16x32_bf16 v[142:145], v[176:179], v[168:171], 0
	s_nop 7
	ds_read_b64_tr_b16 v[172:173], v166 offset:128
	ds_read_b64_tr_b16 v[174:175], v166 offset:1216
	ds_read_b64_tr_b16 v[176:177], v166 offset:160
	ds_read_b64_tr_b16 v[178:179], v166 offset:1248
	s_waitcnt lgkmcnt(0)
	v_mfma_f32_16x16x32_bf16 v[146:149], v[172:175], v[168:171], 0
	v_mfma_f32_16x16x32_bf16 v[150:153], v[176:179], v[168:171], 0
	s_nop 7
	ds_read_b64_tr_b16 v[172:173], v166 offset:192
	ds_read_b64_tr_b16 v[174:175], v166 offset:1280
	ds_read_b64_tr_b16 v[176:177], v166 offset:224
	ds_read_b64_tr_b16 v[178:179], v166 offset:1312
	s_waitcnt lgkmcnt(0)
	v_mfma_f32_16x16x32_bf16 v[154:157], v[172:175], v[168:171], 0
	v_mfma_f32_16x16x32_bf16 v[158:161], v[176:179], v[168:171], 0
	s_nop 7
	ds_read_b64 v[172:173], v184
	ds_read_b64 v[174:175], v184 offset:32
	ds_read_b64 v[176:177], v184 offset:64
	ds_read_b64 v[178:179], v184 offset:96
	s_nop 7
	s_waitcnt lgkmcnt(0)
	v_lshlrev_b32_e32 v168, 16, v172
	v_and_b32_e32 v169, 0xffff0000, v172
	v_lshlrev_b32_e32 v170, 16, v173
	v_and_b32_e32 v171, 0xffff0000, v173
	v_fma_f32 v130, v186, v130, -v168
	v_fma_f32 v131, v186, v131, -v169
	v_fma_f32 v132, v186, v132, -v170
	v_fma_f32 v133, v186, v133, -v171
	v_cvt_pk_bf16_f32 v130, v130, v131
	v_cvt_pk_bf16_f32 v131, v132, v133
	ds_write_b64 v185, v[130:131] offset:40960
	v_lshlrev_b32_e32 v168, 16, v174
	v_and_b32_e32 v169, 0xffff0000, v174
	v_lshlrev_b32_e32 v170, 16, v175
	v_and_b32_e32 v171, 0xffff0000, v175
	v_fma_f32 v134, v186, v134, -v168
	v_fma_f32 v135, v186, v135, -v169
	v_fma_f32 v136, v186, v136, -v170
	v_fma_f32 v137, v186, v137, -v171
	v_cvt_pk_bf16_f32 v134, v134, v135
	v_cvt_pk_bf16_f32 v135, v136, v137
	ds_write_b64 v185, v[134:135] offset:40992
	v_lshlrev_b32_e32 v168, 16, v176
	v_and_b32_e32 v169, 0xffff0000, v176
	v_lshlrev_b32_e32 v170, 16, v177
	v_and_b32_e32 v171, 0xffff0000, v177
	v_fma_f32 v138, v186, v138, -v168
	v_fma_f32 v139, v186, v139, -v169
	v_fma_f32 v140, v186, v140, -v170
	v_fma_f32 v141, v186, v141, -v171
	v_cvt_pk_bf16_f32 v138, v138, v139
	v_cvt_pk_bf16_f32 v139, v140, v141
	ds_write_b64 v185, v[138:139] offset:41024
	v_lshlrev_b32_e32 v168, 16, v178
	v_and_b32_e32 v169, 0xffff0000, v178
	v_lshlrev_b32_e32 v170, 16, v179
	v_and_b32_e32 v171, 0xffff0000, v179
	v_fma_f32 v142, v186, v142, -v168
	v_fma_f32 v143, v186, v143, -v169
	v_fma_f32 v144, v186, v144, -v170
	v_fma_f32 v145, v186, v145, -v171
	v_cvt_pk_bf16_f32 v142, v142, v143
	v_cvt_pk_bf16_f32 v143, v144, v145
	ds_write_b64 v185, v[142:143] offset:41056
	ds_read_b64 v[172:173], v184 offset:128
	ds_read_b64 v[174:175], v184 offset:160
	ds_read_b64 v[176:177], v184 offset:192
	ds_read_b64 v[178:179], v184 offset:224
	s_waitcnt lgkmcnt(0)
	v_lshlrev_b32_e32 v168, 16, v172
	v_and_b32_e32 v169, 0xffff0000, v172
	v_lshlrev_b32_e32 v170, 16, v173
	v_and_b32_e32 v171, 0xffff0000, v173
	v_fma_f32 v146, v186, v146, -v168
	v_fma_f32 v147, v186, v147, -v169
	v_fma_f32 v148, v186, v148, -v170
	v_fma_f32 v149, v186, v149, -v171
	v_cvt_pk_bf16_f32 v146, v146, v147
	v_cvt_pk_bf16_f32 v147, v148, v149
	ds_write_b64 v185, v[146:147] offset:41088
	v_lshlrev_b32_e32 v168, 16, v174
	v_and_b32_e32 v169, 0xffff0000, v174
	v_lshlrev_b32_e32 v170, 16, v175
	v_and_b32_e32 v171, 0xffff0000, v175
	v_fma_f32 v150, v186, v150, -v168
	v_fma_f32 v151, v186, v151, -v169
	v_fma_f32 v152, v186, v152, -v170
	v_fma_f32 v153, v186, v153, -v171
	v_cvt_pk_bf16_f32 v150, v150, v151
	v_cvt_pk_bf16_f32 v151, v152, v153
	ds_write_b64 v185, v[150:151] offset:41120
	v_lshlrev_b32_e32 v168, 16, v176
	v_and_b32_e32 v169, 0xffff0000, v176
	v_lshlrev_b32_e32 v170, 16, v177
	v_and_b32_e32 v171, 0xffff0000, v177
	v_fma_f32 v154, v186, v154, -v168
	v_fma_f32 v155, v186, v155, -v169
	v_fma_f32 v156, v186, v156, -v170
	v_fma_f32 v157, v186, v157, -v171
	v_cvt_pk_bf16_f32 v154, v154, v155
	v_cvt_pk_bf16_f32 v155, v156, v157
	ds_write_b64 v185, v[154:155] offset:41152
	v_lshlrev_b32_e32 v168, 16, v178
	v_and_b32_e32 v169, 0xffff0000, v178
	v_lshlrev_b32_e32 v170, 16, v179
	v_and_b32_e32 v171, 0xffff0000, v179
	v_fma_f32 v158, v186, v158, -v168
	v_fma_f32 v159, v186, v159, -v169
	v_fma_f32 v160, v186, v160, -v170
	v_fma_f32 v161, v186, v161, -v171
	v_cvt_pk_bf16_f32 v158, v158, v159
	v_cvt_pk_bf16_f32 v159, v160, v161
	ds_write_b64 v185, v[158:159] offset:41184
	s_waitcnt lgkmcnt(0)
	s_mov_b64 s[10:11], 0x11101000
	s_mov_b32 s72, 0
	s_ashr_i32 s8, s15, 2
	v_and_or_b32 v142, s8, -16, v165
	v_mul_lo_u32 v250, v142, s33
	v_and_b32_e32 v167, 48, v164
	v_add3_u32 v143, 0, v250, v167
	s_waitcnt lgkmcnt(0)
	s_barrier
	ds_read_b128 v[134:137], v143 offset:40960
	ds_read_b128 v[130:133], v143 offset:41024
	s_waitcnt vmcnt(47) lgkmcnt(1)
	v_mfma_f32_16x16x32_bf16 v[114:117], v[114:117], v[134:137], 0
	v_readlane_b32 s8, v253, 32
	s_waitcnt vmcnt(46) lgkmcnt(0)
	v_mfma_f32_16x16x32_bf16 v[138:141], v[110:113], v[130:133], v[114:117]
	s_nop 4
	ds_read_b128 v[114:117], v143 offset:41088
	ds_read_b128 v[110:113], v143 offset:41152
	s_waitcnt vmcnt(45) lgkmcnt(1)
	v_mfma_f32_16x16x32_bf16 v[106:109], v[106:109], v[114:117], v[138:141]
	s_waitcnt vmcnt(44) lgkmcnt(0)
	v_mfma_f32_16x16x32_bf16 v[102:105], v[102:105], v[110:113], v[106:109]
	s_waitcnt vmcnt(17)
	v_mfma_f32_16x16x32_bf16 v[106:109], v[126:129], v[134:137], 0
	v_add_u32_e32 v126, s8, v142
	v_mfma_f32_16x16x32_bf16 v[106:109], v[122:125], v[130:133], v[106:109]
	v_mov_b64_e32 v[122:123], s[24:25]
	v_mad_i64_i32 v[122:123], s[8:9], v126, s70, v[122:123]
	v_mfma_f32_16x16x32_bf16 v[106:109], v[118:121], v[114:117], v[106:109]
	v_readlane_b32 s8, v253, 29
	s_lshl_b32 s28, s8, 1
	v_lshl_add_u64 v[122:123], v[122:123], 0, s[28:29]
	v_mfma_f32_16x16x32_bf16 v[118:121], v[98:101], v[134:137], 0
	v_lshlrev_b32_e32 v124, 3, v163
	v_mov_b32_e32 v125, v33
	v_lshl_add_u64 v[100:101], v[122:123], 0, v[124:125]
	v_mfma_f32_16x16x32_bf16 v[94:97], v[94:97], v[130:133], v[118:121]
	s_mov_b32 s9, 0x11101000
	v_lshl_add_u64 v[98:99], v[100:101], 0, s[10:11]
	v_add_co_u32_e32 v100, vcc, s9, v100
	v_mfma_f32_16x16x32_bf16 v[90:93], v[90:93], v[114:117], v[94:97]
	s_lshl_b32 s8, s8, 2
	v_addc_co_u32_e32 v101, vcc, 0, v101, vcc
	v_mfma_f32_16x16x32_bf16 v[94:97], v[82:85], v[134:137], 0
	s_add_u32 s10, s2, s8
	s_waitcnt vmcnt(0)
	s_nop 15
	v_mov_b64_e32 v[118:119], v[206:207]
	v_mov_b64_e32 v[120:121], v[208:209]
	v_mov_b64_e32 v[122:123], v[236:237]
	v_mov_b64_e32 v[124:125], v[238:239]
	v_mov_b64_e32 v[84:85], v[204:205]
	v_mov_b64_e32 v[126:127], v[240:241]
	v_mov_b64_e32 v[128:129], v[242:243]
	v_mov_b64_e32 v[82:83], v[244:245]
	v_mfma_f32_16x16x32_bf16 v[78:81], v[78:81], v[130:133], v[94:97]
	s_addc_u32 s11, s14, 0
	s_lshl_b32 s8, s18, 11
	v_mfma_f32_16x16x32_bf16 v[74:77], v[74:77], v[114:117], v[78:81]
	s_mov_b32 s2, 0
	s_waitcnt vmcnt(3)
	v_lshlrev_b32_e32 v94, 16, v84
	s_nop 1
	s_nop 15
	v_mov_b64_e32 v[78:79], v[232:233]
	v_mov_b64_e32 v[80:81], v[234:235]
	v_mfma_f32_16x16x32_bf16 v[70:73], v[70:73], v[134:137], 0
	s_waitcnt vmcnt(0)
	v_mul_f32_e32 v78, v102, v78
	v_mfma_f32_16x16x32_bf16 v[66:69], v[66:69], v[130:133], v[70:73]
	v_mul_f32_e32 v78, v78, v94
	v_mfma_f32_16x16x32_bf16 v[58:61], v[58:61], v[114:117], v[66:69]
	s_nop 2
	v_mul_f32_e32 v70, v103, v79
	v_and_b32_e32 v71, 0xffff0000, v84
	v_mul_f32_e32 v70, v70, v71
	v_mfma_f32_16x16x32_bf16 v[66:69], v[86:89], v[134:137], 0
	v_mul_f32_e32 v71, v104, v80
	v_lshlrev_b32_e32 v72, 16, v85
	v_mul_f32_e32 v71, v71, v72
	v_mfma_f32_16x16x32_bf16 v[62:65], v[62:65], v[130:133], v[66:69]
	v_mul_f32_e32 v72, v105, v81
	v_and_b32_e32 v73, 0xffff0000, v85
	v_cvt_pk_bf16_f32 v70, v78, v70
	v_mfma_f32_16x16x32_bf16 v[50:53], v[50:53], v[114:117], v[62:65]
	s_nop 0
	v_mul_f32_e32 v66, v72, v73
	v_cvt_pk_bf16_f32 v71, v71, v66
	global_store_dwordx2 v[100:101], v[70:71], off
	v_mfma_f32_16x16x32_bf16 v[38:41], v[38:41], v[110:113], v[106:109]
	s_nop 0
	v_mov_b64_e32 v[62:63], v[188:189]
	v_mov_b64_e32 v[64:65], v[190:191]
	v_lshlrev_b32_e32 v66, 16, v118
	v_and_b32_e32 v67, 0xffff0000, v118
	v_mfma_f32_16x16x32_bf16 v[54:57], v[54:57], v[134:137], 0
	v_mfma_f32_16x16x32_bf16 v[20:23], v[20:23], v[110:113], v[90:93]
	s_nop 0
	v_mul_f32_e32 v38, v38, v62
	v_mul_f32_e32 v39, v39, v63
	v_mul_f32_e32 v38, v38, v66
	v_mul_f32_e32 v40, v40, v64
	v_mul_f32_e32 v39, v39, v67
	v_cvt_pk_bf16_f32 v62, v38, v39
	v_lshlrev_b32_e32 v38, 16, v119
	v_mul_f32_e32 v63, v40, v38
	v_mul_f32_e32 v64, v41, v65
	v_mfma_f32_16x16x32_bf16 v[38:41], v[46:49], v[130:133], v[54:57]
	v_and_b32_e32 v65, 0xffff0000, v119
	v_mul_f32_e32 v46, v64, v65
	v_cvt_pk_bf16_f32 v63, v63, v46
	global_store_dwordx2 v[98:99], v[62:63], off offset:32
	v_mfma_f32_16x16x32_bf16 v[38:41], v[42:45], v[114:117], v[38:41]
	v_mov_b64_e32 v[42:43], v[192:193]
	v_mov_b64_e32 v[44:45], v[194:195]
	v_lshlrev_b32_e32 v46, 16, v120
	v_and_b32_e32 v47, 0xffff0000, v120
	v_lshlrev_b32_e32 v48, 16, v121
	v_and_b32_e32 v49, 0xffff0000, v121
	v_mfma_f32_16x16x32_bf16 v[16:19], v[16:19], v[110:113], v[74:77]
	v_mul_f32_e32 v20, v20, v42
	v_mul_f32_e32 v21, v21, v43
	v_mul_f32_e32 v22, v22, v44
	v_mul_f32_e32 v23, v23, v45
	v_mul_f32_e32 v20, v20, v46
	v_mul_f32_e32 v21, v21, v47
	v_mul_f32_e32 v22, v22, v48
	v_mul_f32_e32 v23, v23, v49
	v_cvt_pk_bf16_f32 v20, v20, v21
	v_cvt_pk_bf16_f32 v21, v22, v23
	global_store_dwordx2 v[98:99], v[20:21], off offset:64
	v_mov_b64_e32 v[20:21], v[196:197]
	v_mov_b64_e32 v[22:23], v[198:199]
	v_lshlrev_b32_e32 v42, 16, v122
	v_and_b32_e32 v43, 0xffff0000, v122
	v_lshlrev_b32_e32 v44, 16, v123
	v_and_b32_e32 v45, 0xffff0000, v123
	v_mfma_f32_16x16x32_bf16 v[8:11], v[8:11], v[134:137], 0
	v_mul_f32_e32 v16, v16, v20
	v_mul_f32_e32 v17, v17, v21
	v_mul_f32_e32 v18, v18, v22
	v_mul_f32_e32 v19, v19, v23
	v_mul_f32_e32 v16, v16, v42
	v_mul_f32_e32 v17, v17, v43
	v_mul_f32_e32 v18, v18, v44
	v_mul_f32_e32 v19, v19, v45
	v_cvt_pk_bf16_f32 v16, v16, v17
	v_cvt_pk_bf16_f32 v17, v18, v19
	global_store_dwordx2 v[98:99], v[16:17], off offset:96
	v_mov_b64_e32 v[16:17], v[200:201]
	v_mov_b64_e32 v[18:19], v[202:203]
	v_mfma_f32_16x16x32_bf16 v[20:23], v[34:37], v[110:113], v[58:61]
	v_lshlrev_b32_e32 v34, 16, v124
	v_and_b32_e32 v35, 0xffff0000, v124
	v_lshlrev_b32_e32 v36, 16, v125
	v_and_b32_e32 v37, 0xffff0000, v125
	v_mfma_f32_16x16x32_bf16 v[4:7], v[4:7], v[130:133], v[8:11]
	s_nop 1
	v_mul_f32_e32 v16, v20, v16
	v_mul_f32_e32 v17, v21, v17
	v_mul_f32_e32 v18, v22, v18
	v_mul_f32_e32 v19, v23, v19
	v_mul_f32_e32 v16, v16, v34
	v_mul_f32_e32 v17, v17, v35
	v_mul_f32_e32 v18, v18, v36
	v_mul_f32_e32 v19, v19, v37
	v_cvt_pk_bf16_f32 v16, v16, v17
	v_cvt_pk_bf16_f32 v17, v18, v19
	global_store_dwordx2 v[98:99], v[16:17], off offset:128
	v_mov_b64_e32 v[16:17], v[210:211]
	v_mov_b64_e32 v[18:19], v[212:213]
	v_mfma_f32_16x16x32_bf16 v[20:23], v[28:31], v[110:113], v[50:53]
	v_lshlrev_b32_e32 v28, 16, v126
	v_and_b32_e32 v29, 0xffff0000, v126
	v_lshlrev_b32_e32 v30, 16, v127
	v_and_b32_e32 v31, 0xffff0000, v127
	v_mfma_f32_16x16x32_bf16 v[0:3], v[0:3], v[114:117], v[4:7]
	s_nop 1
	v_mul_f32_e32 v16, v20, v16
	v_mul_f32_e32 v17, v21, v17
	v_mul_f32_e32 v18, v22, v18
	v_mul_f32_e32 v19, v23, v19
	v_mul_f32_e32 v16, v16, v28
	v_mul_f32_e32 v17, v17, v29
	v_mul_f32_e32 v18, v18, v30
	v_mul_f32_e32 v19, v19, v31
	v_cvt_pk_bf16_f32 v16, v16, v17
	v_cvt_pk_bf16_f32 v17, v18, v19
	global_store_dwordx2 v[98:99], v[16:17], off offset:160
	v_mov_b64_e32 v[16:17], v[214:215]
	v_mov_b64_e32 v[18:19], v[216:217]
	v_mfma_f32_16x16x32_bf16 v[20:23], v[24:27], v[110:113], v[38:41]
	v_lshlrev_b32_e32 v24, 16, v128
	v_and_b32_e32 v25, 0xffff0000, v128
	v_lshlrev_b32_e32 v26, 16, v129
	v_and_b32_e32 v27, 0xffff0000, v129
	v_mfma_f32_16x16x32_bf16 v[0:3], v[12:15], v[110:113], v[0:3]
	v_lshlrev_b32_e32 v4, 16, v82
	v_and_b32_e32 v5, 0xffff0000, v82
	v_lshlrev_b32_e32 v6, 16, v83
	v_and_b32_e32 v7, 0xffff0000, v83
	v_mul_f32_e32 v16, v20, v16
	v_mul_f32_e32 v17, v21, v17
	v_mul_f32_e32 v18, v22, v18
	v_mul_f32_e32 v19, v23, v19
	v_mul_f32_e32 v16, v16, v24
	v_mul_f32_e32 v17, v17, v25
	v_mul_f32_e32 v18, v18, v26
	v_mul_f32_e32 v19, v19, v27
	v_cvt_pk_bf16_f32 v16, v16, v17
	v_cvt_pk_bf16_f32 v17, v18, v19
	global_store_dwordx2 v[98:99], v[16:17], off offset:192
	v_mov_b64_e32 v[16:17], v[228:229]
	v_mov_b64_e32 v[18:19], v[230:231]
	v_xor_b32_e32 v20, 16, v226
	v_xor_b32_e32 v21, 32, v226
	v_cmp_lt_i32_e32 vcc, v20, v162
	v_readlane_b32 s10, v251, 33
	v_readlane_b32 s11, v251, 34
	v_cndmask_b32_e32 v20, v226, v20, vcc
	v_cmp_lt_i32_e32 vcc, v21, v162
	s_add_u32 s66, s10, s8
	v_lshlrev_b32_e32 v100, 2, v20
	v_cndmask_b32_e32 v8, v226, v21, vcc
	v_lshlrev_b32_e32 v101, 2, v8
	s_addc_u32 s67, s11, 0
	v_mul_f32_e32 v0, v0, v16
	v_mul_f32_e32 v1, v1, v17
	v_mul_f32_e32 v2, v2, v18
	v_mul_f32_e32 v3, v3, v19
	v_mul_f32_e32 v0, v0, v4
	v_mul_f32_e32 v1, v1, v5
	v_mul_f32_e32 v2, v2, v6
	v_mul_f32_e32 v3, v3, v7
	v_cvt_pk_bf16_f32 v0, v0, v1
	v_cvt_pk_bf16_f32 v1, v2, v3
	global_store_dwordx2 v[98:99], v[0:1], off offset:224
	s_barrier
	s_mov_b32 s48, 0
	s_branch .Lpf_issue
